# speedup vs baseline: 1.0076x; 1.0076x over previous
; __device__ __forceinline__ void softmax_pv(f32x16& s0, f32x16& s1, float& mref, f32x16& negm, float& lsum, f32x16 (&o)[2], LAS float* fac, const bf16x8 (&vf)[2][4], bool first, int r32, int hi) {
;     ...
;     float ps0 = 0.f, ps1 = 0.f;
; #pragma unroll
;     for (int r = 0; r < 16; ++r) { s0[r] = __builtin_amdgcn_exp2f(s0[r]); s1[r] = __builtin_amdgcn_exp2f(s1[r]); ps0 += s0[r]; ps1 += s1[r]; }
;     lsum += ps0 + ps1;
; template <bool DIFF>
; __device__ __forceinline__ void attn_item(const Params& p, int l, int I, LAS unsigned char* lds, const int tid) {
;     ...
;         if (more) { lwrite((st + 1) & 1, 0); lwrite((st + 1) & 1, 1); }
;         __syncthreads();
;     }
.LBB0_458:
	v_add_f32_e32 v48, v49, v48
	v_add_f32_e32 v49, v65, v64
	v_add_f32_e32 v48, v50, v48
	v_add_f32_e32 v49, v66, v49
	v_add_f32_e32 v48, v51, v48
	v_add_f32_e32 v49, v67, v49
	v_add_f32_e32 v48, v52, v48
	v_add_f32_e32 v49, v68, v49
	v_add_f32_e32 v48, v53, v48
	v_add_f32_e32 v49, v69, v49
	v_add_f32_e32 v48, v54, v48
	v_add_f32_e32 v49, v70, v49
	v_add_f32_e32 v48, v55, v48
	v_add_f32_e32 v49, v71, v49
	v_add_f32_e32 v48, v56, v48
	v_add_f32_e32 v49, v72, v49
	v_add_f32_e32 v48, v57, v48
	v_add_f32_e32 v49, v73, v49
	v_add_f32_e32 v48, v58, v48
	v_add_f32_e32 v49, v74, v49
	v_add_f32_e32 v48, v59, v48
	v_add_f32_e32 v49, v75, v49
	v_add_f32_e32 v48, v60, v48
	v_add_f32_e32 v49, v76, v49
	v_add_f32_e32 v48, v61, v48
	v_add_f32_e32 v49, v77, v49
	v_add_f32_e32 v48, v62, v48
	v_add_f32_e32 v49, v78, v49
	v_add_f32_e32 v48, v63, v48
	v_add_f32_e32 v49, v79, v49
	v_add_f32_e32 v48, v49, v48
	s_add_i32 s35, s35, 1
	s_addk_i32 s36, 0x80
	s_add_i32 s37, s37, 2
	v_add_f32_e32 v225, v160, v48
	v_cmp_lt_f32_e32 vcc, 0x47800000, v48
	s_cbranch_vccnz .Lmqb
.Lmqb_c:
	s_cmp_eq_u32 s34, s36
	s_waitcnt lgkmcnt(0)
	s_barrier
	s_cbranch_scc1 .LBB0_482

; #define LAS __attribute__((address_space(3)))
; __device__ __forceinline__ s16x4 vtr(const LAS unsigned char* p) { return __builtin_bit_cast(s16x4, __builtin_amdgcn_ds_read_tr16_b64_v4i16((LAS s16x4*)p)); }
; template <bool DIFF>
; __device__ __forceinline__ void attn_item(const Params& p, int l, int I, LAS unsigned char* lds, const int tid) {
;     ...
;         { bf16x8 kf[6][2];
; #pragma unroll
;           for (int d0 = 0; d0 < 6; ++d0) { kf[d0][0] = *(const LAS bf16x8*)(kbA + d0 * 2048); kf[d0][1] = *(const LAS bf16x8*)(kbA + d0 * 2048 + 512); }
; #pragma unroll
;           for (int d0 = 0; d0 < 6; ++d0) { a0 = __builtin_amdgcn_mfma_f32_32x32x16_bf16(kf[d0][0], qf[d0], a0, 0, 0, 0); a1 = __builtin_amdgcn_mfma_f32_32x32x16_bf16(kf[d0][1], qf[d0], a1, 0, 0, 0); } }
;         { bf16x8 kf[6][2];
; #pragma unroll
;           for (int d0 = 0; d0 < 6; ++d0) { kf[d0][0] = *(const LAS bf16x8*)(kbB + d0 * 2048); kf[d0][1] = *(const LAS bf16x8*)(kbB + d0 * 2048 + 512); }
; #pragma unroll
;           for (int d0 = 0; d0 < 6; ++d0) { b0 = __builtin_amdgcn_mfma_f32_32x32x16_bf16(kf[d0][0], qf[d0], b0, 0, 0, 0); b1 = __builtin_amdgcn_mfma_f32_32x32x16_bf16(kf[d0][1], qf[d0], b1, 0, 0, 0); } }
;         const float m0 = mref1;
;         { bf16x8 vf[2][4]; const LAS unsigned char* vb = sbA + AT_V + vlane;
; #pragma unroll
;           for (int dh = 0; dh < 2; ++dh)
; #pragma unroll
;               for (int k = 0; k < 4; ++k) { const s16x4 lo = vtr(vb + dh * 4096 + k * 1024), hh = vtr(vb + dh * 4096 + k * 1024 + 512);
;                   vf[dh][k] = (bf16x8){lo[0], lo[1], lo[2], lo[3], hh[0], hh[1], hh[2], hh[3]}; }
.LBB0_465:
	s_bitcmp1_b32 s35, 0
	s_cselect_b32 s24, 0xa000, 0
	s_add_i32 s24, s24, 0
	v_add3_u32 v227, s24, v205, v206
	ds_read_b128 v[160:163], v227
	ds_read_b128 v[164:167], v227 offset:512
	ds_read_b128 v[168:171], v227 offset:2048
	ds_read_b128 v[172:175], v227 offset:2560
	ds_read_b128 v[176:179], v227 offset:4096
	ds_read_b128 v[180:183], v227 offset:4608
	ds_read_b128 v[184:187], v227 offset:6144
	ds_read_b128 v[188:191], v227 offset:6656
	ds_read_b128 v[218:221], v227 offset:8192
	ds_read_b128 v[228:231], v227 offset:8704
	ds_read_b128 v[232:235], v227 offset:10240
	ds_read_b128 v[236:239], v227 offset:10752
	v_add_u32_e32 v226, s24, v209
	s_waitcnt lgkmcnt(11)
	v_mfma_f32_32x32x16_bf16 v[80:95], v[160:163], v[128:131], v[32:47]
	ds_read_b128 v[160:163], v227 offset:20480
	s_waitcnt lgkmcnt(11)
	v_mfma_f32_32x32x16_bf16 v[96:111], v[164:167], v[128:131], v[32:47]
	ds_read_b128 v[164:167], v227 offset:20992
	s_waitcnt lgkmcnt(11)
	v_mfma_f32_32x32x16_bf16 v[80:95], v[168:171], v[140:143], v[80:95]
	ds_read_b128 v[168:171], v227 offset:22528
	s_waitcnt lgkmcnt(11)
	v_mfma_f32_32x32x16_bf16 v[96:111], v[172:175], v[140:143], v[96:111]
	ds_read_b128 v[172:175], v227 offset:23040
	s_waitcnt lgkmcnt(11)
	v_mfma_f32_32x32x16_bf16 v[80:95], v[176:179], v[144:147], v[80:95]
	ds_read_b128 v[176:179], v227 offset:24576
	s_waitcnt lgkmcnt(11)
	v_mfma_f32_32x32x16_bf16 v[96:111], v[180:183], v[144:147], v[96:111]
	ds_read_b128 v[180:183], v227 offset:25088
	s_waitcnt lgkmcnt(11)
	v_mfma_f32_32x32x16_bf16 v[80:95], v[184:187], v[148:151], v[80:95]
	ds_read_b128 v[184:187], v227 offset:26624
	s_waitcnt lgkmcnt(11)
	v_mfma_f32_32x32x16_bf16 v[96:111], v[188:191], v[148:151], v[96:111]
	ds_read_b128 v[188:191], v227 offset:27136
	s_waitcnt lgkmcnt(11)
	v_mfma_f32_32x32x16_bf16 v[80:95], v[218:221], v[152:155], v[80:95]
	ds_read_b128 v[218:221], v227 offset:28672
	s_waitcnt lgkmcnt(11)
	v_mfma_f32_32x32x16_bf16 v[96:111], v[228:231], v[152:155], v[96:111]
	ds_read_b128 v[228:231], v227 offset:29184
	s_waitcnt lgkmcnt(11)
	v_mfma_f32_32x32x16_bf16 v[80:95], v[232:235], v[156:159], v[80:95]
	ds_read_b128 v[232:235], v227 offset:30720
	s_waitcnt lgkmcnt(11)
	v_mfma_f32_32x32x16_bf16 v[96:111], v[236:239], v[156:159], v[96:111]
	ds_read_b128 v[236:239], v227 offset:31232
	s_waitcnt lgkmcnt(11)
	v_mfma_f32_32x32x16_bf16 v[48:63], v[160:163], v[128:131], v[32:47]
	s_waitcnt lgkmcnt(10)
	v_mfma_f32_32x32x16_bf16 v[64:79], v[164:167], v[128:131], v[32:47]
	s_waitcnt lgkmcnt(9)
	v_mfma_f32_32x32x16_bf16 v[48:63], v[168:171], v[140:143], v[48:63]
	s_waitcnt lgkmcnt(8)
	v_mfma_f32_32x32x16_bf16 v[64:79], v[172:175], v[140:143], v[64:79]
	s_waitcnt lgkmcnt(7)
	v_mfma_f32_32x32x16_bf16 v[48:63], v[176:179], v[144:147], v[48:63]
	s_waitcnt lgkmcnt(6)
	v_mfma_f32_32x32x16_bf16 v[64:79], v[180:183], v[144:147], v[64:79]
	s_waitcnt lgkmcnt(5)
	v_mfma_f32_32x32x16_bf16 v[48:63], v[184:187], v[148:151], v[48:63]
	s_waitcnt lgkmcnt(4)
	v_mfma_f32_32x32x16_bf16 v[64:79], v[188:191], v[148:151], v[64:79]
	ds_read_b64_tr_b16 v[188:189], v226 offset:12288
	ds_read_b64_tr_b16 v[190:191], v226 offset:12800
	ds_read_b64_tr_b16 v[180:181], v226 offset:13312
	ds_read_b64_tr_b16 v[182:183], v226 offset:13824
	ds_read_b64_tr_b16 v[172:173], v226 offset:14336
	ds_read_b64_tr_b16 v[174:175], v226 offset:14848
	ds_read_b64_tr_b16 v[160:161], v226 offset:15360
	ds_read_b64_tr_b16 v[162:163], v226 offset:15872
	s_waitcnt lgkmcnt(11)
	v_mfma_f32_32x32x16_bf16 v[48:63], v[218:221], v[152:155], v[48:63]
	s_waitcnt lgkmcnt(10)
	v_mfma_f32_32x32x16_bf16 v[64:79], v[228:231], v[152:155], v[64:79]
	s_waitcnt lgkmcnt(9)
	v_mfma_f32_32x32x16_bf16 v[48:63], v[232:235], v[156:159], v[48:63]
	s_waitcnt lgkmcnt(8)
	v_mfma_f32_32x32x16_bf16 v[64:79], v[236:239], v[156:159], v[64:79]
	s_waitcnt lgkmcnt(7)
	ds_read_b64_tr_b16 v[184:185], v226 offset:16384
	ds_read_b64_tr_b16 v[186:187], v226 offset:16896
	ds_read_b64_tr_b16 v[176:177], v226 offset:17408
	ds_read_b64_tr_b16 v[178:179], v226 offset:17920
	ds_read_b64_tr_b16 v[168:169], v226 offset:18432
	ds_read_b64_tr_b16 v[170:171], v226 offset:18944
	ds_read_b64_tr_b16 v[164:165], v226 offset:19456
	ds_read_b64_tr_b16 v[166:167], v226 offset:19968
	s_waitcnt lgkmcnt(14)

; #define LAS __attribute__((address_space(3)))
; __device__ __forceinline__ s16x4 vtr(const LAS unsigned char* p) { return __builtin_bit_cast(s16x4, __builtin_amdgcn_ds_read_tr16_b64_v4i16((LAS s16x4*)p)); }
; __device__ __forceinline__ void softmax_pv(f32x16& s0, f32x16& s1, float& mref, f32x16& negm, float& lsum, f32x16 (&o)[2], LAS float* fac, const bf16x8 (&vf)[2][4], bool first, int r32, int hi) {
;     ...
;     float ps0 = 0.f, ps1 = 0.f;
; #pragma unroll
;     for (int r = 0; r < 16; ++r) { s0[r] = __builtin_amdgcn_exp2f(s0[r]); s1[r] = __builtin_amdgcn_exp2f(s1[r]); ps0 += s0[r]; ps1 += s1[r]; }
;     lsum += ps0 + ps1;
; template <bool DIFF>
; __device__ __forceinline__ void attn_item(const Params& p, int l, int I, LAS unsigned char* lds, const int tid) {
;     ...
;         const float dm = mref1 - m0;
;         if (__builtin_expect(__any(dm != 0.f), 0)) {
; #pragma unroll
;             for (int r = 0; r < 16; ++r) { b0[r] -= dm; b1[r] -= dm; }
;         }
;         { bf16x8 vf[2][4]; const LAS unsigned char* vb = sbB + AT_V + vlane;
; #pragma unroll
;           for (int dh = 0; dh < 2; ++dh)
; #pragma unroll
;               for (int k = 0; k < 4; ++k) { const s16x4 lo = vtr(vb + dh * 4096 + k * 1024), hh = vtr(vb + dh * 4096 + k * 1024 + 512);
;                   vf[dh][k] = (bf16x8){lo[0], lo[1], lo[2], lo[3], hh[0], hh[1], hh[2], hh[3]}; }
;           softmax_pv(b0, b1, mref1, negm1, l1, o1, scr, vf, false, r32, hi); }
.LBB0_468:
	v_add_f32_e32 v80, v229, v228
	v_add_f32_e32 v81, v97, v96
	v_add_f32_e32 v80, v230, v80
	v_add_f32_e32 v81, v98, v81
	v_add_f32_e32 v80, v231, v80
	v_add_f32_e32 v81, v99, v81
	v_add_f32_e32 v80, v84, v80
	v_add_f32_e32 v81, v100, v81
	v_add_f32_e32 v80, v85, v80
	v_add_f32_e32 v81, v101, v81
	v_add_f32_e32 v80, v86, v80
	v_add_f32_e32 v81, v102, v81
	v_add_f32_e32 v80, v87, v80
	v_add_f32_e32 v81, v103, v81
	v_add_f32_e32 v80, v88, v80
	v_add_f32_e32 v81, v104, v81
	v_add_f32_e32 v80, v89, v80
	v_add_f32_e32 v81, v105, v81
	v_add_f32_e32 v80, v90, v80
	v_add_f32_e32 v81, v106, v81
	v_add_f32_e32 v80, v91, v80
	v_add_f32_e32 v81, v107, v81
	v_add_f32_e32 v80, v92, v80
	v_add_f32_e32 v81, v108, v81
	v_add_f32_e32 v80, v93, v80
	v_add_f32_e32 v81, v109, v81
	v_add_f32_e32 v80, v94, v80
	v_add_f32_e32 v81, v110, v81
	v_add_f32_e32 v80, v95, v80
	v_add_f32_e32 v81, v111, v81
	v_add_f32_e32 v80, v81, v80
	v_add_f32_e32 v160, v225, v80
	v_cmp_lt_f32_e32 vcc, 0x47800000, v80
	s_cbranch_vccnz .Lmqa
.Lmqa_c:
	ds_read_b64_tr_b16 v[108:109], v226 offset:32768
	ds_read_b64_tr_b16 v[110:111], v226 offset:33280
	ds_read_b64_tr_b16 v[100:101], v226 offset:33792
	ds_read_b64_tr_b16 v[102:103], v226 offset:34304
	ds_read_b64_tr_b16 v[92:93], v226 offset:34816
	ds_read_b64_tr_b16 v[94:95], v226 offset:35328
	ds_read_b64_tr_b16 v[80:81], v226 offset:35840
	ds_read_b64_tr_b16 v[82:83], v226 offset:36352
	ds_read_b64_tr_b16 v[104:105], v226 offset:36864
	ds_read_b64_tr_b16 v[106:107], v226 offset:37376
	ds_read_b64_tr_b16 v[96:97], v226 offset:37888
	ds_read_b64_tr_b16 v[98:99], v226 offset:38400
	ds_read_b64_tr_b16 v[88:89], v226 offset:38912
	ds_read_b64_tr_b16 v[90:91], v226 offset:39424
	ds_read_b64_tr_b16 v[84:85], v226 offset:39936
	ds_read_b64_tr_b16 v[86:87], v226 offset:40448

; __device__ __forceinline__ int crow(int r, int hi) { return (r & 3) + 8 * (r >> 2) + 4 * hi; }
; __device__ __forceinline__ void softmax_pv(f32x16& s0, f32x16& s1, float& mref, f32x16& negm, float& lsum, f32x16 (&o)[2], LAS float* fac, const bf16x8 (&vf)[2][4], bool first, int r32, int hi) {
;     ...
;     if (__builtin_expect(first || __any(mx > 16.0f), 0)) {
;         const float d = first ? mx : fmaxf(mx, 0.f);
;         const float f = __builtin_amdgcn_exp2f(-d);
;         lsum *= f; mref += d;
; #pragma unroll
;         for (int r = 0; r < 16; ++r) { s0[r] -= d; s1[r] -= d; negm[r] = -mref; }
;         if (hi == 0) fac[r32] = f;
;         asm volatile("s_waitcnt lgkmcnt(0)" ::: "memory");
; #pragma unroll
;         for (int r = 0; r < 16; ++r) { const float ff = fac[crow(r, hi)]; o[0][r] *= ff; o[1][r] *= ff; }
;     }
; template <bool DIFF>
; __device__ __forceinline__ void attn_item(const Params& p, int l, int I, LAS unsigned char* lds, const int tid) {
;     ...
;         const float dm = mref1 - m0;
;         if (__builtin_expect(__any(dm != 0.f), 0)) {
; #pragma unroll
;             for (int r = 0; r < 16; ++r) { b0[r] -= dm; b1[r] -= dm; }
;         }
.Lmqa:
	v_mov_b32_e32 v82, v80
	v_mov_b32_e32 v83, v80
	s_nop 1
	v_permlane32_swap_b32_e32 v82, v83
	v_add_f32_e32 v82, v82, v83
	v_log_f32_e32 v84, v82
	s_nop 0
	v_ceil_f32_e32 v84, v84
	v_max_f32_e32 v84, 0, v84
	v_exp_f32_e64 v85, -v84
	s_nop 7
	s_and_saveexec_b64 s[24:25], s[8:9]
	ds_write_b32 v208, v85
	s_or_b64 exec, exec, s[24:25]
	v_add_f32_e32 v211, v211, v84
	v_mul_f32_e32 v160, v160, v85
	v_sub_f32_e32 v48, v48, v84
	v_sub_f32_e32 v49, v49, v84
	v_sub_f32_e32 v50, v50, v84
	v_sub_f32_e32 v51, v51, v84
	v_sub_f32_e32 v52, v52, v84
	v_sub_f32_e32 v53, v53, v84
	v_sub_f32_e32 v54, v54, v84
	v_sub_f32_e32 v55, v55, v84
	v_sub_f32_e32 v56, v56, v84
	v_sub_f32_e32 v57, v57, v84
	v_sub_f32_e32 v58, v58, v84
	v_sub_f32_e32 v59, v59, v84
	v_sub_f32_e32 v60, v60, v84
	v_sub_f32_e32 v61, v61, v84
	v_sub_f32_e32 v62, v62, v84
	v_sub_f32_e32 v63, v63, v84
	v_sub_f32_e32 v64, v64, v84
	v_sub_f32_e32 v65, v65, v84
	v_sub_f32_e32 v66, v66, v84
	v_sub_f32_e32 v67, v67, v84
	v_sub_f32_e32 v68, v68, v84
	v_sub_f32_e32 v69, v69, v84
	v_sub_f32_e32 v70, v70, v84
	v_sub_f32_e32 v71, v71, v84
	v_sub_f32_e32 v72, v72, v84
	v_sub_f32_e32 v73, v73, v84
	v_sub_f32_e32 v74, v74, v84
	v_sub_f32_e32 v75, v75, v84
	v_sub_f32_e32 v76, v76, v84
	v_sub_f32_e32 v77, v77, v84
	v_sub_f32_e32 v78, v78, v84
	v_sub_f32_e32 v79, v79, v84
	v_xor_b32_e32 v32, 0x80000000, v211
	v_mov_b32_e32 v33, v32
	v_mov_b32_e32 v34, v32
	v_mov_b32_e32 v35, v32
	v_mov_b32_e32 v36, v32
	v_mov_b32_e32 v37, v32
	v_mov_b32_e32 v38, v32
	v_mov_b32_e32 v39, v32
	v_mov_b32_e32 v40, v32
	v_mov_b32_e32 v41, v32
	v_mov_b32_e32 v42, v32
	v_mov_b32_e32 v43, v32
	v_mov_b32_e32 v44, v32
	v_mov_b32_e32 v45, v32
	v_mov_b32_e32 v46, v32
	v_mov_b32_e32 v47, v32
	s_waitcnt lgkmcnt(0)
	ds_read_b128 v[88:91], v210
	ds_read_b128 v[92:95], v210 offset:32
	s_waitcnt lgkmcnt(0)
	v_pk_mul_f32 v[16:17], v[16:17], v[88:89]
	v_pk_mul_f32 v[18:19], v[18:19], v[90:91]
	v_pk_mul_f32 v[20:21], v[20:21], v[92:93]
	v_pk_mul_f32 v[22:23], v[22:23], v[94:95]
	v_pk_mul_f32 v[0:1], v[0:1], v[88:89]
	v_pk_mul_f32 v[2:3], v[2:3], v[90:91]
	v_pk_mul_f32 v[4:5], v[4:5], v[92:93]
	v_pk_mul_f32 v[6:7], v[6:7], v[94:95]
	ds_read_b128 v[88:91], v210 offset:64
	ds_read_b128 v[92:95], v210 offset:96
	s_waitcnt lgkmcnt(0)
	v_pk_mul_f32 v[24:25], v[24:25], v[88:89]
	v_pk_mul_f32 v[26:27], v[26:27], v[90:91]
	v_pk_mul_f32 v[28:29], v[28:29], v[92:93]
	v_pk_mul_f32 v[30:31], v[30:31], v[94:95]
	v_pk_mul_f32 v[8:9], v[8:9], v[88:89]
	v_pk_mul_f32 v[10:11], v[10:11], v[90:91]
	v_pk_mul_f32 v[12:13], v[12:13], v[92:93]
	v_pk_mul_f32 v[14:15], v[14:15], v[94:95]
	s_branch .Lmqa_c
.Lmqb:
	v_mov_b32_e32 v50, v48
	v_mov_b32_e32 v51, v48
	s_nop 1
	v_permlane32_swap_b32_e32 v50, v51
	v_add_f32_e32 v50, v50, v51
	v_log_f32_e32 v52, v50
	s_nop 0
	v_ceil_f32_e32 v52, v52
	v_max_f32_e32 v52, 0, v52
	v_exp_f32_e64 v53, -v52
	s_nop 7
	s_and_saveexec_b64 s[24:25], s[8:9]
	ds_write_b32 v208, v53
	s_or_b64 exec, exec, s[24:25]
	v_add_f32_e32 v211, v211, v52
	v_mul_f32_e32 v225, v225, v53
	v_xor_b32_e32 v32, 0x80000000, v211
	v_mov_b32_e32 v33, v32
	v_mov_b32_e32 v34, v32
	v_mov_b32_e32 v35, v32
	v_mov_b32_e32 v36, v32
	v_mov_b32_e32 v37, v32
	v_mov_b32_e32 v38, v32
	v_mov_b32_e32 v39, v32
	v_mov_b32_e32 v40, v32
	v_mov_b32_e32 v41, v32
	v_mov_b32_e32 v42, v32
	v_mov_b32_e32 v43, v32
	v_mov_b32_e32 v44, v32
	v_mov_b32_e32 v45, v32
	v_mov_b32_e32 v46, v32
	v_mov_b32_e32 v47, v32
	s_waitcnt lgkmcnt(0)
	ds_read_b128 v[56:59], v210
	ds_read_b128 v[60:63], v210 offset:32
	s_waitcnt lgkmcnt(0)
	v_pk_mul_f32 v[16:17], v[16:17], v[56:57]
	v_pk_mul_f32 v[18:19], v[18:19], v[58:59]
	v_pk_mul_f32 v[20:21], v[20:21], v[60:61]
	v_pk_mul_f32 v[22:23], v[22:23], v[62:63]
	v_pk_mul_f32 v[0:1], v[0:1], v[56:57]
	v_pk_mul_f32 v[2:3], v[2:3], v[58:59]
	v_pk_mul_f32 v[4:5], v[4:5], v[60:61]
	v_pk_mul_f32 v[6:7], v[6:7], v[62:63]
	ds_read_b128 v[56:59], v210 offset:64
	ds_read_b128 v[60:63], v210 offset:96
	s_waitcnt lgkmcnt(0)
	v_pk_mul_f32 v[24:25], v[24:25], v[56:57]
	v_pk_mul_f32 v[26:27], v[26:27], v[58:59]
	v_pk_mul_f32 v[28:29], v[28:29], v[60:61]
	v_pk_mul_f32 v[30:31], v[30:31], v[62:63]
	v_pk_mul_f32 v[8:9], v[8:9], v[56:57]
	v_pk_mul_f32 v[10:11], v[10:11], v[58:59]
	v_pk_mul_f32 v[12:13], v[12:13], v[60:61]
	v_pk_mul_f32 v[14:15], v[14:15], v[62:63]
	s_branch .Lmqb_c
